# C2 row loop: common-path vmcnt(0) store drains removed; the rare conv-state load paths wait for their own loads
# baseline (speedup 1.0000x reference)
; __device__ __forceinline__ float siluf_(float x) { return x * __builtin_amdgcn_rcpf(1.0f + __expf(-x)); }
; __device__ __forceinline__ u32x4 pack8(const float* f) { u32x4 w; w.x = cvtpk(f[0], f[1]); w.y = cvtpk(f[2], f[3]); w.z = cvtpk(f[4], f[5]); w.w = cvtpk(f[6], f[7]); return w; }
; __device__ __forceinline__ bf16x8 pack8(const f32x4& a, const f32x4& b) { u32x4 w; w.x = cpk(a.x, a.y); w.y = cpk(a.z, a.w); w.z = cpk(b.x, b.y); w.w = cpk(b.z, b.w); return __builtin_bit_cast(bf16x8, w); }
; __global__ void __launch_bounds__(NWAVES * 64, 2) mk_fwd(Args args) {
;     ...
;                         for (int j = 0; j < 2; ++j) {
;                             const int c = j * 512 + lane * 8;
;                             float u0[8], u1[8], u2[8], fa[8], fb[8];
;                             unpack8(rcc[j][0], fa); unpack8(rcx[j][0], fb);
; #pragma unroll
;                             for (int e = 0; e < 8; ++e) u0[e] = fa[e] * fb[e];
;                             if (t >= 1) { unpack8(rcc[j][1], fa); unpack8(rcx[j][1], fb);
; #pragma unroll
;                                 for (int e = 0; e < 8; ++e) u1[e] = fa[e] * fb[e]; }
;                             else {
; #pragma unroll
;                                 for (int e = 0; e < 8; ++e) u1[e] = smp ? cbuf[CONVD + c + e] : 0.f; }
;                             if (t >= 2) { unpack8(rcc[j][2], fa); unpack8(rcx[j][2], fb);
; #pragma unroll
;                                 for (int e = 0; e < 8; ++e) u2[e] = fa[e] * fb[e]; }
;                             else {
; #pragma unroll
;                                 for (int e = 0; e < 8; ++e) u2[e] = smp ? cbuf[t * CONVD + c + e] : 0.f; }
;                             float vb[8], vg[8], y[8];
;                             unpack8(rvb[j], vb); unpack8(rvg[j], vg);
; #pragma unroll
;                             for (int e = 0; e < 8; ++e) { const float yy = cb[c + e] + u2[e] * cw[c + e] + u1[e] * cw[CONVD + c + e] + u0[e] * cw[2 * CONVD + c + e];
;                                 y[e] = vb[e] * yy * siluf_(vg[e]); }
;                             *(u32x4*)(hmix + (size_t)m * DM + 3072 + c) = pack8(y);
;                             if (t >= T - 2) { float* co = cv_out + (size_t)(t - (T - 2)) * CONVD + c;
;                                 *(f32x4*)co = (f32x4){u0[0], u0[1], u0[2], u0[3]}; *(f32x4*)(co + 4) = (f32x4){u0[4], u0[5], u0[6], u0[7]}; }
;                         }
.LBB0_551:
	s_waitcnt vmcnt(0)
	s_mov_b64 s[6:7], 0
.LBB0_552:
	s_and_b64 vcc, exec, s[6:7]
	s_cbranch_vccz .LBB0_554
	v_lshlrev_b32_e32 v84, 16, v80
	v_and_b32_e32 v85, 0xffff0000, v80
	v_lshlrev_b32_e32 v86, 16, v76
	v_and_b32_e32 v87, 0xffff0000, v76
	v_lshlrev_b32_e32 v80, 16, v81
	v_and_b32_e32 v81, 0xffff0000, v81
	v_lshlrev_b32_e32 v76, 16, v77
	v_and_b32_e32 v77, 0xffff0000, v77
	v_pk_mul_f32 v[162:163], v[80:81], v[76:77]
	v_lshlrev_b32_e32 v76, 16, v82
	v_and_b32_e32 v77, 0xffff0000, v82
	v_lshlrev_b32_e32 v80, 16, v78
	v_and_b32_e32 v81, 0xffff0000, v78
	v_pk_mul_f32 v[156:157], v[76:77], v[80:81]
	v_lshlrev_b32_e32 v76, 16, v83
	v_and_b32_e32 v77, 0xffff0000, v83
	v_lshlrev_b32_e32 v78, 16, v79
	v_and_b32_e32 v79, 0xffff0000, v79
	v_pk_mul_f32 v[172:173], v[84:85], v[86:87]
	v_pk_mul_f32 v[154:155], v[76:77], v[78:79]
.LBB0_554:
	s_and_b64 s[6:7], s[8:9], exec
	s_cselect_b32 s6, 30, 0xffe
	v_mov_b32_e32 v2, s6
	v_sub_co_u32_e64 v2, s[6:7], s39, v2
	v_lshlrev_b32_e32 v2, 10, v2
	v_lshlrev_b64 v[76:77], 2, v[2:3]
	v_lshl_add_u64 v[146:147], s[68:69], 0, v[76:77]
	v_lshlrev_b32_e32 v76, 16, v72
	v_and_b32_e32 v77, 0xffff0000, v72
	v_lshlrev_b32_e32 v78, 16, v68
	v_and_b32_e32 v79, 0xffff0000, v68
	v_lshlrev_b32_e32 v72, 16, v73
	v_and_b32_e32 v73, 0xffff0000, v73
	v_lshlrev_b32_e32 v68, 16, v69
	v_and_b32_e32 v69, 0xffff0000, v69
	v_pk_mul_f32 v[76:77], v[76:77], v[78:79]
	v_pk_mul_f32 v[78:79], v[72:73], v[68:69]
	v_lshlrev_b32_e32 v68, 16, v74
	v_and_b32_e32 v69, 0xffff0000, v74
	v_lshlrev_b32_e32 v72, 16, v70
	v_and_b32_e32 v73, 0xffff0000, v70
	v_pk_mul_f32 v[68:69], v[68:69], v[72:73]
	v_lshlrev_b32_e32 v72, 16, v75
	v_and_b32_e32 v73, 0xffff0000, v75
	v_lshlrev_b32_e32 v70, 16, v71
	v_and_b32_e32 v71, 0xffff0000, v71
	v_pk_mul_f32 v[70:71], v[72:73], v[70:71]
	v_mov_b64_e32 v[72:73], v[222:223]
	v_mov_b64_e32 v[74:75], v[224:225]
	v_mov_b64_e32 v[92:93], v[226:227]
	v_mov_b64_e32 v[94:95], v[228:229]
	v_mov_b64_e32 v[80:81], v[230:231]
	v_mov_b64_e32 v[82:83], v[232:233]
	v_mov_b64_e32 v[104:105], v[234:235]
	v_mov_b64_e32 v[106:107], v[236:237]
	v_mov_b64_e32 v[84:85], v[240:241]
	v_mov_b64_e32 v[86:87], v[242:243]
	v_mov_b64_e32 v[96:97], v[244:245]
	v_mov_b64_e32 v[98:99], v[246:247]
	v_mov_b64_e32 v[88:89], v[184:185]
	v_mov_b64_e32 v[90:91], v[186:187]
	v_mov_b64_e32 v[100:101], v[194:195]
	v_mov_b64_e32 v[102:103], v[248:249]
	v_mov_b32_e32 v164, v160
	v_mov_b32_e32 v165, v76
	v_mov_b32_e32 v151, v70
	v_mov_b32_e32 v149, v71
	v_mov_b32_e32 v182, v96
	v_fma_f32 v2, v172, v104, v92
	v_mov_b32_e32 v183, v100
	v_mov_b32_e32 v100, v97
	v_and_b32_e32 v97, 0xffff0000, v60
	v_pk_mul_f32 v[164:165], v[164:165], v[182:183]
	v_lshlrev_b32_e32 v183, 16, v60
	v_mul_f32_e32 v60, 0xbfb8aa3b, v97
	v_exp_f32_e32 v60, v60
	v_fma_f32 v96, v173, v105, v93
	v_mov_b32_e32 v92, v161
	v_mov_b32_e32 v93, v77
	v_pk_mul_f32 v[92:93], v[92:93], v[100:101]
	v_add_f32_e32 v60, 1.0, v60
	v_add_f32_e32 v92, v96, v92
	v_add_f32_e32 v92, v92, v93
	v_rcp_f32_e32 v93, v60
	v_and_b32_e32 v96, 0xffff0000, v64
	v_lshlrev_b32_e32 v182, 16, v64
	v_fma_f32 v60, v162, v106, v94
	v_pk_mul_f32 v[92:93], v[92:93], v[96:97]
	v_mov_b32_e32 v96, v98
	v_mul_f32_e32 v64, v92, v93
	v_mov_b32_e32 v92, v158
	v_mov_b32_e32 v93, v78
	v_mov_b32_e32 v97, v102
	v_pk_mul_f32 v[92:93], v[92:93], v[96:97]
	v_lshlrev_b32_e32 v97, 16, v61
	v_add_f32_e32 v60, v60, v92
	v_add_f32_e32 v92, v60, v93
	v_mul_f32_e32 v60, 0xbfb8aa3b, v97
	v_exp_f32_e32 v60, v60
	v_lshlrev_b32_e32 v96, 16, v65
	v_mov_b32_e32 v102, v99
	v_fmac_f32_e32 v95, v163, v107
	v_add_f32_e32 v60, 1.0, v60
	v_rcp_f32_e32 v93, v60
	v_and_b32_e32 v94, 0xffff0000, v65
	v_fma_f32 v72, v156, v80, v72
	v_fmac_f32_e32 v75, v155, v83
	v_pk_mul_f32 v[92:93], v[92:93], v[96:97]
	v_mov_b32_e32 v96, v159
	v_mov_b32_e32 v97, v79
	v_pk_mul_f32 v[96:97], v[96:97], v[102:103]
	v_add_f32_e32 v2, v2, v164
	v_add_f32_e32 v60, v95, v96
	v_and_b32_e32 v95, 0xffff0000, v61
	v_mul_f32_e32 v61, 0xbfb8aa3b, v95
	v_exp_f32_e32 v61, v61
	v_add_f32_e32 v60, v60, v97
	v_add_f32_e32 v164, v2, v165
	v_mul_f32_e32 v2, 0xbfb8aa3b, v183
	v_add_f32_e32 v61, 1.0, v61
	v_rcp_f32_e32 v61, v61
	v_exp_f32_e32 v2, v2
	v_mul_f32_e32 v92, v92, v93
	v_pk_mul_f32 v[60:61], v[60:61], v[94:95]
	s_nop 0
	v_mul_f32_e32 v65, v60, v61
	v_mov_b32_e32 v60, v152
	v_mov_b32_e32 v61, v68
	v_mov_b32_e32 v94, v84
	v_mov_b32_e32 v95, v88
	v_pk_mul_f32 v[60:61], v[60:61], v[94:95]
	v_lshlrev_b32_e32 v95, 16, v62
	v_add_f32_e32 v60, v72, v60
	v_add_f32_e32 v60, v60, v61
	v_mul_f32_e32 v61, 0xbfb8aa3b, v95
	v_exp_f32_e32 v61, v61
	v_lshlrev_b32_e32 v94, 16, v66
	v_mov_b32_e32 v88, v85
	v_fma_f32 v72, v157, v81, v73
	v_add_f32_e32 v61, 1.0, v61
	v_rcp_f32_e32 v61, v61
	v_and_b32_e32 v73, 0xffff0000, v62
	v_fma_f32 v62, v154, v82, v74
	v_add_f32_e32 v2, 1.0, v2
	v_pk_mul_f32 v[60:61], v[60:61], v[94:95]
	v_rcp_f32_e32 v165, v2
	v_mul_f32_e32 v80, v60, v61
	v_mov_b32_e32 v60, v153
	v_mov_b32_e32 v61, v69
	v_pk_mul_f32 v[60:61], v[60:61], v[88:89]
	v_pk_mul_f32 v[164:165], v[164:165], v[182:183]
	v_add_f32_e32 v60, v72, v60
	v_add_f32_e32 v60, v60, v61
	v_mul_f32_e32 v61, 0xbfb8aa3b, v73
	v_exp_f32_e32 v61, v61
	v_and_b32_e32 v72, 0xffff0000, v66
	v_mul_f32_e32 v2, v164, v165
	v_add_f32_e32 v61, 1.0, v61
	v_rcp_f32_e32 v61, v61
	s_nop 0
	v_pk_mul_f32 v[60:61], v[60:61], v[72:73]
	s_nop 0
	v_mul_f32_e32 v66, v60, v61
	v_mov_b32_e32 v60, v86
	v_mov_b32_e32 v61, v90
	v_pk_mul_f32 v[60:61], v[150:151], v[60:61]
	v_lshlrev_b32_e32 v73, 16, v63
	v_add_f32_e32 v60, v62, v60
	v_add_f32_e32 v60, v60, v61
	v_mul_f32_e32 v61, 0xbfb8aa3b, v73
	v_exp_f32_e32 v61, v61
	v_lshlrev_b32_e32 v72, 16, v67
	v_mov_b32_e32 v90, v87
	v_and_b32_e32 v63, 0xffff0000, v63
	v_add_f32_e32 v61, 1.0, v61
	v_rcp_f32_e32 v61, v61
	v_and_b32_e32 v62, 0xffff0000, v67
	v_pk_mul_f32 v[60:61], v[60:61], v[72:73]
	s_nop 0
	v_mul_f32_e32 v72, v60, v61
	v_pk_mul_f32 v[60:61], v[148:149], v[90:91]
	s_nop 0
	v_add_f32_e32 v60, v75, v60
	v_add_f32_e32 v60, v60, v61
	v_mul_f32_e32 v61, 0xbfb8aa3b, v63
	v_exp_f32_e32 v61, v61
	s_nop 0
	v_add_f32_e32 v61, 1.0, v61
	v_rcp_f32_e32 v61, v61
	s_nop 0
	v_pk_mul_f32 v[60:61], v[60:61], v[62:63]
	s_nop 0
	v_mul_f32_e32 v63, v60, v61
	v_cvt_pk_bf16_f32 v60, v2, v64
	v_cvt_pk_bf16_f32 v61, v92, v65
	v_cvt_pk_bf16_f32 v62, v80, v66
	v_lshl_add_u64 v[80:81], v[124:125], 0, s[48:49]
	v_add_co_u32_e32 v64, vcc, 0xaf01000, v80
	v_cvt_pk_bf16_f32 v63, v72, v63
	s_nop 1
	v_addc_co_u32_e32 v65, vcc, 0, v81, vcc
	s_and_b64 vcc, exec, s[6:7]
	global_store_dwordx4 v[64:65], v[60:63], off offset:2048
	s_cbranch_vccnz .LBB0_556
	v_readfirstlane_b32 s66, v146
	v_readfirstlane_b32 s67, v147
	s_nop 4
	global_store_dwordx4 v144, v[76:79], s[66:67]
	global_store_dwordx4 v144, v[68:71], s[66:67] offset:16

; __device__ __forceinline__ float siluf_(float x) { return x * __builtin_amdgcn_rcpf(1.0f + __expf(-x)); }
; __device__ __forceinline__ u32x4 pack8(const float* f) { u32x4 w; w.x = cvtpk(f[0], f[1]); w.y = cvtpk(f[2], f[3]); w.z = cvtpk(f[4], f[5]); w.w = cvtpk(f[6], f[7]); return w; }
; __device__ __forceinline__ bf16x8 pack8(const f32x4& a, const f32x4& b) { u32x4 w; w.x = cpk(a.x, a.y); w.y = cpk(a.z, a.w); w.z = cpk(b.x, b.y); w.w = cpk(b.z, b.w); return __builtin_bit_cast(bf16x8, w); }
; __global__ void __launch_bounds__(NWAVES * 64, 2) mk_fwd(Args args) {
;     ...
;                         for (int j = 0; j < 2; ++j) {
;                             const int c = j * 512 + lane * 8;
;                             float u0[8], u1[8], u2[8], fa[8], fb[8];
;                             unpack8(rcc[j][0], fa); unpack8(rcx[j][0], fb);
; #pragma unroll
;                             for (int e = 0; e < 8; ++e) u0[e] = fa[e] * fb[e];
;                             if (t >= 1) { unpack8(rcc[j][1], fa); unpack8(rcx[j][1], fb);
; #pragma unroll
;                                 for (int e = 0; e < 8; ++e) u1[e] = fa[e] * fb[e]; }
;                             else {
; #pragma unroll
;                                 for (int e = 0; e < 8; ++e) u1[e] = smp ? cbuf[CONVD + c + e] : 0.f; }
;                             if (t >= 2) { unpack8(rcc[j][2], fa); unpack8(rcx[j][2], fb);
; #pragma unroll
;                                 for (int e = 0; e < 8; ++e) u2[e] = fa[e] * fb[e]; }
;                             else {
; #pragma unroll
;                                 for (int e = 0; e < 8; ++e) u2[e] = smp ? cbuf[t * CONVD + c + e] : 0.f; }
;                             float vb[8], vg[8], y[8];
;                             unpack8(rvb[j], vb); unpack8(rvg[j], vg);
; #pragma unroll
;                             for (int e = 0; e < 8; ++e) { const float yy = cb[c + e] + u2[e] * cw[c + e] + u1[e] * cw[CONVD + c + e] + u0[e] * cw[2 * CONVD + c + e];
;                                 y[e] = vb[e] * yy * siluf_(vg[e]); }
;                             *(u32x4*)(hmix + (size_t)m * DM + 3072 + c) = pack8(y);
;                             if (t >= T - 2) { float* co = cv_out + (size_t)(t - (T - 2)) * CONVD + c;
;                                 *(f32x4*)co = (f32x4){u0[0], u0[1], u0[2], u0[3]}; *(f32x4*)(co + 4) = (f32x4){u0[4], u0[5], u0[6], u0[7]}; }
;                         }
.LBB0_592:
	s_waitcnt vmcnt(0)
	s_mov_b64 s[4:5], 0
.LBB0_593:
	s_and_b64 vcc, exec, s[4:5]
	s_cbranch_vccz .LBB0_595
	v_lshlrev_b32_e32 v52, 16, v48
	v_and_b32_e32 v53, 0xffff0000, v48
	v_lshlrev_b32_e32 v54, 16, v44
	v_and_b32_e32 v55, 0xffff0000, v44
	v_lshlrev_b32_e32 v48, 16, v49
	v_and_b32_e32 v49, 0xffff0000, v49
	v_lshlrev_b32_e32 v44, 16, v45
	v_and_b32_e32 v45, 0xffff0000, v45
	v_pk_mul_f32 v[92:93], v[48:49], v[44:45]
	v_lshlrev_b32_e32 v44, 16, v50
	v_and_b32_e32 v45, 0xffff0000, v50
	v_lshlrev_b32_e32 v48, 16, v46
	v_and_b32_e32 v49, 0xffff0000, v46
	v_pk_mul_f32 v[86:87], v[44:45], v[48:49]
	v_lshlrev_b32_e32 v44, 16, v51
	v_and_b32_e32 v45, 0xffff0000, v51
	v_lshlrev_b32_e32 v46, 16, v47
	v_and_b32_e32 v47, 0xffff0000, v47
	v_pk_mul_f32 v[94:95], v[52:53], v[54:55]
	v_pk_mul_f32 v[84:85], v[44:45], v[46:47]
.LBB0_595:
	v_lshlrev_b32_e32 v44, 16, v36
	v_and_b32_e32 v45, 0xffff0000, v36
	v_lshlrev_b32_e32 v46, 16, v40
	v_and_b32_e32 v47, 0xffff0000, v40
	v_lshlrev_b32_e32 v36, 16, v37
	v_and_b32_e32 v37, 0xffff0000, v37
	v_lshlrev_b32_e32 v40, 16, v41
	v_and_b32_e32 v41, 0xffff0000, v41
	v_pk_mul_f32 v[44:45], v[44:45], v[46:47]
	v_pk_mul_f32 v[46:47], v[36:37], v[40:41]
	v_lshlrev_b32_e32 v36, 16, v38
	v_and_b32_e32 v37, 0xffff0000, v38
	v_lshlrev_b32_e32 v40, 16, v42
	v_and_b32_e32 v41, 0xffff0000, v42
	v_pk_mul_f32 v[36:37], v[36:37], v[40:41]
	v_lshlrev_b32_e32 v38, 16, v39
	v_and_b32_e32 v39, 0xffff0000, v39
	v_lshlrev_b32_e32 v40, 16, v43
	v_and_b32_e32 v41, 0xffff0000, v43
	v_pk_mul_f32 v[38:39], v[38:39], v[40:41]
	ds_read_b128 v[40:43], v181
	ds_read_b128 v[60:63], v181 offset:1024
	ds_read_b128 v[48:51], v181 offset:2048
	ds_read_b128 v[72:75], v181 offset:3072
	ds_read_b128 v[52:55], v181 offset:4096
	ds_read_b128 v[64:67], v181 offset:5120
	ds_read_b128 v[56:59], v181 offset:6144
	ds_read_b128 v[68:71], v181 offset:7168
	s_waitcnt lgkmcnt(0)
	v_mov_b32_e32 v96, v90
	v_mov_b32_e32 v97, v44
	v_mov_b32_e32 v79, v38
	v_mov_b32_e32 v77, v39
	v_mov_b32_e32 v98, v64
	v_fma_f32 v2, v94, v72, v60
	v_mov_b32_e32 v99, v68
	v_fma_f32 v64, v95, v73, v61
	v_mov_b32_e32 v60, v91
	v_mov_b32_e32 v61, v45
	v_mov_b32_e32 v68, v65
	v_pk_mul_f32 v[60:61], v[60:61], v[68:69]
	v_and_b32_e32 v65, 0xffff0000, v32
	v_pk_mul_f32 v[96:97], v[96:97], v[98:99]
	v_lshlrev_b32_e32 v98, 16, v28
	v_add_f32_e32 v60, v64, v60
	v_and_b32_e32 v64, 0xffff0000, v28
	v_mul_f32_e32 v28, 0xbfb8aa3b, v65
	v_exp_f32_e32 v28, v28
	v_add_f32_e32 v60, v60, v61
	v_lshlrev_b32_e32 v99, 16, v32
	v_fma_f32 v32, v92, v74, v62
	v_add_f32_e32 v28, 1.0, v28
	v_rcp_f32_e32 v61, v28
	v_fmac_f32_e32 v63, v93, v75
	v_and_b32_e32 v62, 0xffff0000, v29
	v_add_f32_e32 v2, v2, v96
	v_pk_mul_f32 v[60:61], v[60:61], v[64:65]
	v_mov_b32_e32 v64, v66
	v_mul_f32_e32 v28, v60, v61
	v_mov_b32_e32 v60, v88
	v_mov_b32_e32 v61, v46
	v_mov_b32_e32 v65, v70
	v_pk_mul_f32 v[60:61], v[60:61], v[64:65]
	v_lshlrev_b32_e32 v65, 16, v33
	v_add_f32_e32 v32, v32, v60
	v_add_f32_e32 v60, v32, v61
	v_mul_f32_e32 v32, 0xbfb8aa3b, v65
	v_exp_f32_e32 v32, v32
	v_lshlrev_b32_e32 v64, 16, v29
	v_mov_b32_e32 v70, v67
	v_add_f32_e32 v96, v2, v97
	v_add_f32_e32 v32, 1.0, v32
	v_rcp_f32_e32 v61, v32
	v_mul_f32_e32 v2, 0xbfb8aa3b, v99
	v_exp_f32_e32 v2, v2
	v_fmac_f32_e32 v43, v85, v51
	v_pk_mul_f32 v[60:61], v[60:61], v[64:65]
	v_add_f32_e32 v2, 1.0, v2
	v_mul_f32_e32 v32, v60, v61
	v_mov_b32_e32 v60, v89
	v_mov_b32_e32 v61, v47
	v_pk_mul_f32 v[60:61], v[60:61], v[70:71]
	v_rcp_f32_e32 v97, v2
	v_add_f32_e32 v60, v63, v60
	v_and_b32_e32 v63, 0xffff0000, v33
	v_mul_f32_e32 v29, 0xbfb8aa3b, v63
	v_exp_f32_e32 v29, v29
	v_add_f32_e32 v60, v60, v61
	v_fma_f32 v33, v86, v48, v40
	v_fma_f32 v48, v87, v49, v41
	v_add_f32_e32 v29, 1.0, v29
	v_rcp_f32_e32 v61, v29
	v_mov_b32_e32 v40, v83
	v_mov_b32_e32 v41, v37
	v_and_b32_e32 v49, 0xffff0000, v34
	v_pk_mul_f32 v[60:61], v[60:61], v[62:63]
	v_mov_b32_e32 v63, v56
	v_mov_b32_e32 v56, v53
	v_mul_f32_e32 v29, v60, v61
	v_mov_b32_e32 v60, v82
	v_mov_b32_e32 v61, v36
	v_mov_b32_e32 v62, v52
	v_pk_mul_f32 v[40:41], v[40:41], v[56:57]
	v_pk_mul_f32 v[60:61], v[60:61], v[62:63]
	v_lshlrev_b32_e32 v62, 16, v30
	v_add_f32_e32 v40, v48, v40
	v_and_b32_e32 v48, 0xffff0000, v30
	v_mul_f32_e32 v30, 0xbfb8aa3b, v49
	v_exp_f32_e32 v30, v30
	v_add_f32_e32 v40, v40, v41
	v_add_f32_e32 v33, v33, v60
	v_lshlrev_b32_e32 v63, 16, v34
	v_add_f32_e32 v30, 1.0, v30
	v_rcp_f32_e32 v41, v30
	v_fma_f32 v30, v84, v50, v42
	v_add_f32_e32 v60, v33, v61
	v_mul_f32_e32 v33, 0xbfb8aa3b, v63
	v_pk_mul_f32 v[40:41], v[40:41], v[48:49]
	v_lshlrev_b32_e32 v49, 16, v35
	v_mul_f32_e32 v52, v40, v41
	v_mov_b32_e32 v40, v54
	v_mov_b32_e32 v41, v58
	v_pk_mul_f32 v[40:41], v[78:79], v[40:41]
	v_and_b32_e32 v35, 0xffff0000, v35
	v_add_f32_e32 v30, v30, v40
	v_add_f32_e32 v40, v30, v41
	v_mul_f32_e32 v30, 0xbfb8aa3b, v49
	v_exp_f32_e32 v30, v30
	v_exp_f32_e32 v33, v33
	v_lshlrev_b32_e32 v48, 16, v31
	v_and_b32_e32 v34, 0xffff0000, v31
	v_mul_f32_e32 v31, 0xbfb8aa3b, v35
	v_add_f32_e32 v30, 1.0, v30
	v_exp_f32_e32 v31, v31
	v_rcp_f32_e32 v41, v30
	v_add_f32_e32 v33, 1.0, v33
	v_rcp_f32_e32 v61, v33
	v_add_f32_e32 v31, 1.0, v31
	v_pk_mul_f32 v[40:41], v[40:41], v[48:49]
	v_mov_b32_e32 v58, v55
	v_rcp_f32_e32 v31, v31
	v_mul_f32_e32 v42, v40, v41
	v_pk_mul_f32 v[40:41], v[76:77], v[58:59]
	v_pk_mul_f32 v[96:97], v[96:97], v[98:99]
	v_add_f32_e32 v30, v43, v40
	v_pk_mul_f32 v[60:61], v[60:61], v[62:63]
	v_add_f32_e32 v30, v30, v41
	v_mul_f32_e32 v2, v96, v97
	v_mul_f32_e32 v33, v60, v61
	v_pk_mul_f32 v[30:31], v[30:31], v[34:35]
	v_cvt_pk_bf16_f32 v28, v2, v28
	v_cvt_pk_bf16_f32 v29, v32, v29
	v_add_co_u32_e32 v32, vcc, 0xaf01000, v80
	v_mul_f32_e32 v31, v30, v31
	v_cvt_pk_bf16_f32 v30, v33, v52
	s_nop 0
	v_addc_co_u32_e32 v33, vcc, 0, v81, vcc
	s_andn2_b64 vcc, exec, s[6:7]
	v_cvt_pk_bf16_f32 v31, v42, v31
	global_store_dwordx4 v[32:33], v[28:31], off offset:3072
	s_cbranch_vccnz .LBB0_500
	v_readfirstlane_b32 s4, v146
	v_readfirstlane_b32 s5, v147
	s_nop 4
	global_store_dwordx4 v144, v[44:47], s[4:5] offset:2048
	global_store_dwordx4 v144, v[36:39], s[4:5] offset:2064
	s_branch .LBB0_500
